# k19: k16a + EpiRes row-statistics exchange loads batched (1 round trip instead of 3) + acquire fence only for the last-arriving owner
# speedup vs baseline: 1.0072x; 1.0072x over previous
; #define ER_BAR() do { asm volatile("s_waitcnt lgkmcnt(0)" ::: "memory"); __builtin_amdgcn_s_barrier(); asm volatile("" ::: "memory"); } while (0)
;     __device__ __forceinline__ void operator()(const f32x4 (&acc)[2][2][4][2], const Unit& u, int wr, int wc, int fr, int fq, const float (&)[8]) const {
;     ...
;         asm volatile("s_waitcnt vmcnt(0)" ::: "memory");
;         ER_BAR();
;         if (tid < 256) { const unsigned* xs = (const unsigned*)xch + (size_t)(u.pm * BM + tid) * 4; float tot = 0.f;
; #pragma unroll
;             for (int t = 0; t < 4; ++t) tot += __uint_as_float(__hip_atomic_load(xs + t, __ATOMIC_RELAXED, __HIP_MEMORY_SCOPE_AGENT));
;             S[tid] = rsqrtf(tot * (1.0f / 1024.0f) + EPS) * scale; }
.LBB0_165:
	s_waitcnt vmcnt(0)
	s_waitcnt lgkmcnt(0)
	s_barrier
	s_and_saveexec_b64 s[6:7], s[46:47]
	s_cbranch_execz .LBB0_167
	v_readlane_b32 s12, v255, 35
	v_readlane_b32 s13, v255, 36
	s_nop 1
	v_lshl_add_u64 v[212:213], v[230:231], 4, s[12:13]
	global_load_dword v214, v[212:213], off sc1
	global_load_dword v215, v[212:213], off offset:4 sc1
	global_load_dword v216, v[212:213], off offset:8 sc1
	global_load_dword v217, v[212:213], off offset:12 sc1
	s_waitcnt vmcnt(0)
	v_add_f32_e32 v214, 0, v214
	v_add_f32_e32 v214, v214, v215
	v_add_f32_e32 v214, v214, v216
	v_add_f32_e32 v212, v214, v217
	v_fmamk_f32 v212, v212, 0x3a800000, v235
	v_cmp_gt_f32_e32 vcc, s96, v212
	v_mul_f32_e32 v213, 0x4b800000, v212
	s_nop 0
	v_cndmask_b32_e32 v212, v212, v213, vcc
	v_rsq_f32_e32 v212, v212
	s_nop 0
	v_mul_f32_e32 v213, 0x45800000, v212
	v_cndmask_b32_e32 v212, v212, v213, vcc
	v_lshl_add_u32 v213, v243, 2, v233
	ds_write_b32 v213, v212 offset:4096

; #define ER_BAR() do { asm volatile("s_waitcnt lgkmcnt(0)" ::: "memory"); __builtin_amdgcn_s_barrier(); asm volatile("" ::: "memory"); } while (0)
;     __device__ __forceinline__ void operator()(const f32x4 (&acc)[2][2][4][2], const Unit& u, int wr, int wc, int fr, int fq, const float (&)[8]) const {
;     ...
;             if (tid < 256) __hip_atomic_store((unsigned*)xnp + ((size_t)(u.pm * BM + tid) * 4 + u.pn), __float_as_uint((P[tid * 4] + P[tid * 4 + 1]) + (P[tid * 4 + 2] + P[tid * 4 + 3])), __ATOMIC_RELAXED, __HIP_MEMORY_SCOPE_AGENT);
;             asm volatile("s_waitcnt vmcnt(0)" ::: "memory");
;             ER_BAR();
;             if (tid == 0) { const unsigned old = __hip_atomic_fetch_add(cnt + 6 * 128 * 64 + 64 * u.pm, 1u, __ATOMIC_RELAXED, __HIP_MEMORY_SCOPE_AGENT); __builtin_amdgcn_fence(__ATOMIC_ACQUIRE, "agent"); S[0] = (old == 3u) ? 1.0f : 0.0f; }
;             asm volatile("s_waitcnt vmcnt(0)" ::: "memory");
;             ER_BAR();
;             if (S[0] != 0.0f && tid < 256) { const unsigned* xs = (const unsigned*)xnp + (size_t)(u.pm * BM + tid) * 4; float tot = 0.f;
; #pragma unroll
;                 for (int t = 0; t < 4; ++t) tot += __uint_as_float(__hip_atomic_load(xs + t, __ATOMIC_RELAXED, __HIP_MEMORY_SCOPE_AGENT));
;                 rr[u.pm * BM + tid] = rsqrtf(tot * (1.0f / 1024.0f) + EPS); }
.LBB0_188:
	s_or_b64 exec, exec, s[44:45]
	s_waitcnt vmcnt(0)
	v_readfirstlane_b32 s8, v1
	s_waitcnt lgkmcnt(0)
	s_nop 1
	s_cmp_lg_u32 s8, 3
	s_cbranch_scc1 .Ler_noinv_a
	buffer_inv sc1
.Ler_noinv_a:
	v_add_u32_e32 v0, s8, v0
	v_cmp_eq_u32_e32 vcc, 3, v0
	s_nop 1
	v_cndmask_b32_e64 v0, 0, 1.0, vcc
	ds_write_b32 v233, v0 offset:4096
.LBB0_189:
	s_or_b64 exec, exec, s[6:7]
	s_waitcnt vmcnt(0)
	s_waitcnt lgkmcnt(0)
	s_barrier
	ds_read_b32 v0, v233 offset:4096
	s_waitcnt lgkmcnt(0)
	v_cmp_neq_f32_e32 vcc, 0, v0
	s_and_b64 s[12:13], s[46:47], vcc
	s_and_saveexec_b64 s[6:7], s[12:13]
	s_cbranch_execz .LBB0_191
	v_lshl_add_u64 v[0:1], v[230:231], 4, s[70:71]
	global_load_dword v2, v[0:1], off sc1
	global_load_dword v3, v[0:1], off offset:4 sc1
	global_load_dword v4, v[0:1], off offset:8 sc1
	global_load_dword v5, v[0:1], off offset:12 sc1
	s_waitcnt vmcnt(0)
	v_add_f32_e32 v2, 0, v2
	v_add_f32_e32 v2, v2, v3
	v_add_f32_e32 v2, v2, v4
	v_add_f32_e32 v0, v2, v5
	v_fmamk_f32 v0, v0, 0x3a800000, v235
	v_cmp_gt_f32_e32 vcc, s96, v0
	v_mul_f32_e32 v1, 0x4b800000, v0
	s_nop 0
	v_cndmask_b32_e32 v0, v0, v1, vcc
	v_rsq_f32_e32 v0, v0
	s_nop 0
	v_mul_f32_e32 v1, 0x45800000, v0
	v_cndmask_b32_e32 v2, v0, v1, vcc
	v_lshl_add_u64 v[0:1], v[230:231], 2, s[30:31]
	global_store_dword v[0:1], v2, off

; #define ER_BAR() do { asm volatile("s_waitcnt lgkmcnt(0)" ::: "memory"); __builtin_amdgcn_s_barrier(); asm volatile("" ::: "memory"); } while (0)
;     __device__ __forceinline__ void operator()(const f32x4 (&acc)[2][2][4][2], const Unit& u, int wr, int wc, int fr, int fq, const float (&)[8]) const {
;     ...
;         asm volatile("s_waitcnt vmcnt(0)" ::: "memory");
;         ER_BAR();
;         if (tid < 256) { const unsigned* xs = (const unsigned*)xch + (size_t)(u.pm * BM + tid) * 4; float tot = 0.f;
; #pragma unroll
;             for (int t = 0; t < 4; ++t) tot += __uint_as_float(__hip_atomic_load(xs + t, __ATOMIC_RELAXED, __HIP_MEMORY_SCOPE_AGENT));
;             S[tid] = rsqrtf(tot * (1.0f / 1024.0f) + EPS) * scale; }
.LBB0_799:
	s_waitcnt vmcnt(0)
	s_waitcnt lgkmcnt(0)
	s_barrier
	s_and_saveexec_b64 s[6:7], s[46:47]
	s_cbranch_execz .LBB0_801
	v_add_u32_e32 v232, s72, v245
	v_readlane_b32 s12, v255, 35
	v_ashrrev_i32_e32 v233, 31, v232
	v_readlane_b32 s13, v255, 36
	s_nop 1
	v_lshl_add_u64 v[232:233], v[232:233], 4, s[12:13]
	global_load_dword v212, v[232:233], off sc1
	global_load_dword v213, v[232:233], off offset:4 sc1
	global_load_dword v250, v[232:233], off offset:8 sc1
	global_load_dword v251, v[232:233], off offset:12 sc1
	s_waitcnt vmcnt(0)
	v_add_f32_e32 v212, 0, v212
	v_add_f32_e32 v212, v212, v213
	v_add_f32_e32 v212, v212, v250
	v_add_f32_e32 v212, v212, v251
	v_fmamk_f32 v212, v212, 0x3a800000, v235
	v_cmp_gt_f32_e32 vcc, s96, v212
	v_mul_f32_e32 v213, 0x4b800000, v212
	s_nop 0
	v_cndmask_b32_e32 v212, v212, v213, vcc
	v_rsq_f32_e32 v212, v212
	s_nop 0
	v_mul_f32_e32 v213, 0x45800000, v212
	v_cndmask_b32_e32 v212, v212, v213, vcc
	v_mul_f32_e32 v212, 0.5, v212
	v_lshl_add_u32 v213, v245, 2, v243
	ds_write_b32 v213, v212 offset:4096

; #define ER_BAR() do { asm volatile("s_waitcnt lgkmcnt(0)" ::: "memory"); __builtin_amdgcn_s_barrier(); asm volatile("" ::: "memory"); } while (0)
;     __device__ __forceinline__ void operator()(const f32x4 (&acc)[2][2][4][2], const Unit& u, int wr, int wc, int fr, int fq, const float (&)[8]) const {
;     ...
;             if (tid < 256) __hip_atomic_store((unsigned*)xnp + ((size_t)(u.pm * BM + tid) * 4 + u.pn), __float_as_uint((P[tid * 4] + P[tid * 4 + 1]) + (P[tid * 4 + 2] + P[tid * 4 + 3])), __ATOMIC_RELAXED, __HIP_MEMORY_SCOPE_AGENT);
;             asm volatile("s_waitcnt vmcnt(0)" ::: "memory");
;             ER_BAR();
;             if (tid == 0) { const unsigned old = __hip_atomic_fetch_add(cnt + 6 * 128 * 64 + 64 * u.pm, 1u, __ATOMIC_RELAXED, __HIP_MEMORY_SCOPE_AGENT); __builtin_amdgcn_fence(__ATOMIC_ACQUIRE, "agent"); S[0] = (old == 3u) ? 1.0f : 0.0f; }
;             asm volatile("s_waitcnt vmcnt(0)" ::: "memory");
;             ER_BAR();
;             if (S[0] != 0.0f && tid < 256) { const unsigned* xs = (const unsigned*)xnp + (size_t)(u.pm * BM + tid) * 4; float tot = 0.f;
; #pragma unroll
;                 for (int t = 0; t < 4; ++t) tot += __uint_as_float(__hip_atomic_load(xs + t, __ATOMIC_RELAXED, __HIP_MEMORY_SCOPE_AGENT));
;                 rr[u.pm * BM + tid] = rsqrtf(tot * (1.0f / 1024.0f) + EPS); }
.LBB0_888:
	s_or_b64 exec, exec, s[44:45]
	s_waitcnt vmcnt(0)
	v_readfirstlane_b32 s12, v3
	s_waitcnt lgkmcnt(0)
	s_nop 1
	s_cmp_lg_u32 s12, 3
	s_cbranch_scc1 .Ler_noinv_b
	buffer_inv sc1
.Ler_noinv_b:
	v_add_u32_e32 v2, s12, v2
	v_cmp_eq_u32_e32 vcc, 3, v2
	s_nop 1
	v_cndmask_b32_e64 v2, 0, 1.0, vcc
	ds_write_b32 v243, v2 offset:4096
.LBB0_889:
	s_or_b64 exec, exec, s[6:7]
	s_waitcnt vmcnt(0)
	s_waitcnt lgkmcnt(0)
	s_barrier
	ds_read_b32 v2, v243 offset:4096
	s_waitcnt lgkmcnt(0)
	v_cmp_neq_f32_e32 vcc, 0, v2
	s_and_b64 s[12:13], s[46:47], vcc
	s_and_saveexec_b64 s[6:7], s[12:13]
	s_cbranch_execz .LBB0_891
	v_lshl_add_u64 v[2:3], v[0:1], 4, s[68:69]
	global_load_dword v4, v[2:3], off sc1
	global_load_dword v5, v[2:3], off offset:4 sc1
	global_load_dword v6, v[2:3], off offset:8 sc1
	global_load_dword v7, v[2:3], off offset:12 sc1
	v_lshl_add_u64 v[0:1], v[0:1], 2, s[30:31]
	s_waitcnt vmcnt(0)
	v_add_f32_e32 v4, 0, v4
	v_add_f32_e32 v4, v4, v5
	v_add_f32_e32 v4, v4, v6
	v_add_f32_e32 v2, v4, v7
	v_fmamk_f32 v2, v2, 0x3a800000, v235
	v_cmp_gt_f32_e32 vcc, s96, v2
	v_mul_f32_e32 v3, 0x4b800000, v2
	s_nop 0
	v_cndmask_b32_e32 v2, v2, v3, vcc
	v_rsq_f32_e32 v2, v2
	s_nop 0
	v_mul_f32_e32 v3, 0x45800000, v2
	v_cndmask_b32_e32 v2, v2, v3, vcc
	global_store_dword v[0:1], v2, off
